# attention A: deferred O/l rescale (running max only raised when it grows by >4 in log2 units; wave-uniform skip of the 32 rescale multiplies)
# speedup vs baseline: 1.0087x; 1.0087x over previous
; template <int DQK, bool MB> ...
;     ...
;             float alpha2[2];
; #pragma unroll
;             for (int ct = 0; ct < 2; ++ct) {
;                 float mx = -INFINITY;
; #pragma unroll
;                 for (int ks = 0; ks < 4; ++ks)
; #pragma unroll
;                     for (int j = 0; j < 4; ++j) mx = fmaxf(mx, s[ks][ct][j]);
;                 mx = fmaxf(mx, __shfl_xor(mx, 16)); mx = fmaxf(mx, __shfl_xor(mx, 32));
;                 const float mnew = fmaxf(mrow[ct], mx), alpha = __builtin_amdgcn_exp2f(mrow[ct] - mnew);
;                 mrow[ct] = mnew;
;                 float ps = 0.f;
; #pragma unroll
;                 for (int ks = 0; ks < 4; ++ks)
; #pragma unroll
;                     for (int j = 0; j < 4; ++j) { const float p = __builtin_amdgcn_exp2f(s[ks][ct][j] - mnew); s[ks][ct][j] = p; ps += p; }
;                 lsum[ct] = lsum[ct] * alpha + ps; alpha2[ct] = alpha;
;             }
;             {
; #pragma unroll
;                 for (int ct = 0; ct < 2; ++ct)
; #pragma unroll
;                     for (int dt = 0; dt < 8; ++dt) o[ct][dt] *= alpha2[ct];
;             }
.LBB0_496:
	s_nop 1
	v_max3_f32 v170, v148, s41, v149
	v_max3_f32 v170, v170, v150, v151
	v_max3_f32 v170, v170, v156, v157
	v_and_b32_e32 v169, 64, v195
	v_max3_f32 v170, v170, v158, v159
	v_xor_b32_e32 v168, 16, v195
	v_add_u32_e32 v169, 64, v169
	v_max3_f32 v170, v170, v160, v161
	v_cmp_lt_i32_e32 vcc, v168, v169
	v_max3_f32 v170, v170, v162, v163
	v_max3_f32 v170, v170, v152, v153
	v_cndmask_b32_e32 v168, v195, v168, vcc
	v_lshlrev_b32_e32 v168, 2, v168
	v_max3_f32 v170, v170, v154, v155
	ds_bpermute_b32 v171, v168, v170
	v_xor_b32_e32 v172, 32, v195
	v_cmp_lt_i32_e32 vcc, v172, v169
	s_mul_i32 s0, s22, 0x4400
	s_nop 0
	v_cndmask_b32_e32 v169, v195, v172, vcc
	v_lshlrev_b32_e32 v172, 2, v169
	s_waitcnt lgkmcnt(0)
	v_max_f32_e32 v169, v171, v171
	v_max_f32_e32 v169, v170, v169
	ds_bpermute_b32 v170, v172, v169
	s_waitcnt lgkmcnt(0)
	v_max3_f32 v205, v185, v169, v170
	v_sub_f32_e32 v241, v205, v185
	v_cmp_lt_f32_e64 s[98:99], 4.0, v241
	s_nop 1
	v_cndmask_b32_e64 v205, v185, v205, s[98:99]
	v_sub_f32_e32 v148, v148, v205
	v_exp_f32_e32 v169, v148
	v_sub_f32_e32 v148, v149, v205
	v_exp_f32_e32 v171, v148
	v_sub_f32_e32 v148, v150, v205
	v_exp_f32_e32 v173, v148
	v_sub_f32_e32 v148, v151, v205
	v_exp_f32_e32 v175, v148
	v_sub_f32_e32 v148, v156, v205
	v_max3_f32 v150, v136, s41, v137
	v_exp_f32_e32 v183, v148
	v_sub_f32_e32 v148, v157, v205
	v_max3_f32 v150, v150, v138, v139
	v_sub_f32_e32 v170, v185, v205
	v_exp_f32_e32 v185, v148
	v_sub_f32_e32 v148, v158, v205
	v_max3_f32 v150, v150, v144, v145
	v_exp_f32_e32 v187, v148
	v_sub_f32_e32 v148, v159, v205
	v_max3_f32 v150, v150, v146, v147
	v_exp_f32_e32 v189, v148
	v_sub_f32_e32 v148, v160, v205
	v_max3_f32 v150, v150, v132, v133
	v_exp_f32_e32 v149, v148
	v_sub_f32_e32 v148, v161, v205
	v_max3_f32 v150, v150, v134, v135
	v_exp_f32_e32 v151, v148
	v_sub_f32_e32 v148, v162, v205
	v_max3_f32 v150, v150, v140, v141
	v_exp_f32_e32 v157, v148
	v_sub_f32_e32 v148, v163, v205
	v_max3_f32 v150, v150, v142, v143
	v_exp_f32_e32 v159, v148
	v_sub_f32_e32 v148, v152, v205
	ds_bpermute_b32 v152, v168, v150
	v_exp_f32_e32 v207, v170
	v_exp_f32_e32 v161, v148
	v_sub_f32_e32 v148, v153, v205
	v_exp_f32_e32 v153, v148
	s_waitcnt lgkmcnt(0)
	v_max_f32_e32 v152, v152, v152
	v_max_f32_e32 v150, v150, v152
	ds_bpermute_b32 v152, v172, v150
	v_sub_f32_e32 v148, v154, v205
	v_exp_f32_e32 v163, v148
	v_sub_f32_e32 v148, v155, v205
	v_exp_f32_e32 v155, v148
	s_waitcnt lgkmcnt(0)
	v_max3_f32 v222, v184, v150, v152
	v_sub_f32_e32 v242, v222, v184
	v_cmp_lt_f32_e64 s[100:101], 4.0, v242
	s_nop 1
	v_cndmask_b32_e64 v222, v184, v222, s[100:101]
	v_sub_f32_e32 v136, v136, v222
	v_exp_f32_e32 v168, v136
	v_sub_f32_e32 v136, v137, v222
	v_exp_f32_e32 v170, v136
	v_sub_f32_e32 v136, v138, v222
	v_exp_f32_e32 v172, v136
	v_sub_f32_e32 v136, v139, v222
	v_exp_f32_e32 v174, v136
	v_sub_f32_e32 v136, v144, v222
	v_exp_f32_e32 v182, v136
	v_sub_f32_e32 v136, v145, v222
	v_sub_f32_e32 v206, v184, v222
	v_exp_f32_e32 v184, v136
	v_sub_f32_e32 v136, v146, v222
	v_exp_f32_e32 v186, v136
	v_sub_f32_e32 v136, v147, v222
	v_exp_f32_e32 v188, v136
	v_pk_add_f32 v[136:137], v[168:169], 0 op_sel_hi:[1,0]
	v_sub_f32_e32 v132, v132, v222
	v_pk_add_f32 v[136:137], v[170:171], v[136:137]
	v_exp_f32_e32 v148, v132
	v_pk_add_f32 v[136:137], v[172:173], v[136:137]
	v_sub_f32_e32 v132, v133, v222
	v_pk_add_f32 v[136:137], v[174:175], v[136:137]
	v_exp_f32_e32 v150, v132
	v_sub_f32_e32 v132, v134, v222
	v_pk_add_f32 v[136:137], v[182:183], v[136:137]
	v_exp_f32_e32 v156, v132
	v_sub_f32_e32 v132, v135, v222
	v_pk_add_f32 v[136:137], v[184:185], v[136:137]
	v_exp_f32_e32 v158, v132
	v_sub_f32_e32 v132, v140, v222
	v_pk_add_f32 v[136:137], v[186:187], v[136:137]
	v_exp_f32_e32 v160, v132
	v_sub_f32_e32 v132, v141, v222
	v_pk_add_f32 v[136:137], v[188:189], v[136:137]
	v_exp_f32_e32 v152, v132
	v_sub_f32_e32 v132, v142, v222
	v_pk_add_f32 v[136:137], v[148:149], v[136:137]
	v_exp_f32_e32 v162, v132
	v_sub_f32_e32 v132, v143, v222
	v_exp_f32_e32 v154, v132
	v_pk_add_f32 v[132:133], v[150:151], v[136:137]
	v_exp_f32_e32 v206, v206
	v_pk_add_f32 v[132:133], v[156:157], v[132:133]
	v_cvt_pk_bf16_f32 v134, v183, v185
	v_pk_add_f32 v[132:133], v[158:159], v[132:133]
	v_cvt_pk_bf16_f32 v135, v187, v189
	v_pk_add_f32 v[132:133], v[160:161], v[132:133]
	v_pk_add_f32 v[132:133], v[152:153], v[132:133]
	v_pk_add_f32 v[132:133], v[162:163], v[132:133]
	v_pk_add_f32 v[132:133], v[154:155], v[132:133]
	v_pk_fma_f32 v[180:181], v[180:181], v[206:207], v[132:133]
	v_cvt_pk_bf16_f32 v132, v169, v171
	v_add_u32_e32 v169, s0, v204
	v_cvt_pk_bf16_f32 v133, v173, v175
	v_add_u32_e32 v173, 0xc000, v169
	v_add_u32_e32 v175, 0xc800, v169
	v_add_u32_e32 v183, 0xd000, v169
	v_add_u32_e32 v185, 0xd800, v169
	v_add_u32_e32 v187, 0xe000, v169
	v_add_u32_e32 v189, 0xe800, v169
	v_add_u32_e32 v223, 0xf000, v169
	v_add_u32_e32 v225, 0xf800, v169
	s_or_b64 s[98:99], s[98:99], s[100:101]
	s_cmp_eq_u64 s[98:99], 0
	s_cbranch_scc1 .Llazy_a_skip
	v_pk_mul_f32 v[30:31], v[30:31], v[206:207] op_sel_hi:[1,0]
	v_pk_mul_f32 v[28:29], v[28:29], v[206:207] op_sel_hi:[1,0]
	v_pk_mul_f32 v[26:27], v[26:27], v[206:207] op_sel_hi:[1,0]
	v_pk_mul_f32 v[24:25], v[24:25], v[206:207] op_sel_hi:[1,0]
	v_pk_mul_f32 v[22:23], v[22:23], v[206:207] op_sel_hi:[1,0]
	v_pk_mul_f32 v[20:21], v[20:21], v[206:207] op_sel_hi:[1,0]
	v_pk_mul_f32 v[18:19], v[18:19], v[206:207] op_sel_hi:[1,0]
	v_pk_mul_f32 v[16:17], v[16:17], v[206:207] op_sel_hi:[1,0]
	v_pk_mul_f32 v[14:15], v[14:15], v[206:207] op_sel_hi:[1,0]
	v_pk_mul_f32 v[12:13], v[12:13], v[206:207] op_sel_hi:[1,0]
	v_pk_mul_f32 v[10:11], v[10:11], v[206:207] op_sel_hi:[1,0]
	v_pk_mul_f32 v[8:9], v[8:9], v[206:207] op_sel_hi:[1,0]
	v_pk_mul_f32 v[6:7], v[6:7], v[206:207] op_sel_hi:[1,0]
	v_pk_mul_f32 v[4:5], v[4:5], v[206:207] op_sel_hi:[1,0]
	v_pk_mul_f32 v[2:3], v[2:3], v[206:207] op_sel_hi:[1,0]
	v_pk_mul_f32 v[0:1], v[0:1], v[206:207] op_sel_hi:[1,0]
	v_pk_mul_f32 v[62:63], v[62:63], v[206:207] op_sel:[0,1]
	v_pk_mul_f32 v[60:61], v[60:61], v[206:207] op_sel:[0,1]
	v_pk_mul_f32 v[58:59], v[58:59], v[206:207] op_sel:[0,1]
	v_pk_mul_f32 v[56:57], v[56:57], v[206:207] op_sel:[0,1]
	v_pk_mul_f32 v[54:55], v[54:55], v[206:207] op_sel:[0,1]
	v_pk_mul_f32 v[52:53], v[52:53], v[206:207] op_sel:[0,1]
	v_pk_mul_f32 v[50:51], v[50:51], v[206:207] op_sel:[0,1]
	v_pk_mul_f32 v[48:49], v[48:49], v[206:207] op_sel:[0,1]
	v_pk_mul_f32 v[46:47], v[46:47], v[206:207] op_sel:[0,1]
	v_pk_mul_f32 v[44:45], v[44:45], v[206:207] op_sel:[0,1]
	v_pk_mul_f32 v[42:43], v[42:43], v[206:207] op_sel:[0,1]
	v_pk_mul_f32 v[40:41], v[40:41], v[206:207] op_sel:[0,1]
	v_pk_mul_f32 v[38:39], v[38:39], v[206:207] op_sel:[0,1]
	v_pk_mul_f32 v[36:37], v[36:37], v[206:207] op_sel:[0,1]
	v_pk_mul_f32 v[34:35], v[34:35], v[206:207] op_sel:[0,1]
	v_pk_mul_f32 v[32:33], v[32:33], v[206:207] op_sel:[0,1]
; #define LAS __attribute__((address_space(3)))
; DI unsigned pk2(float lo, float hi) { f32v2 v = {lo, hi}; bf16v2 b = __builtin_convertvector(v, bf16v2); return __builtin_bit_cast(unsigned, b); }
; template <int DQK, bool MB> ...
;     ...
;             for (int kb2 = 0; kb2 < 2; ++kb2) {
;                 bf16x8 pb[2];
; #pragma unroll
;                 for (int ct = 0; ct < 2; ++ct) { u32x4 w; w.x = pk2(s[2 * kb2][ct][0], s[2 * kb2][ct][1]); w.y = pk2(s[2 * kb2][ct][2], s[2 * kb2][ct][3]);
;                     w.z = pk2(s[2 * kb2 + 1][ct][0], s[2 * kb2 + 1][ct][1]); w.w = pk2(s[2 * kb2 + 1][ct][2], s[2 * kb2 + 1][ct][3]); pb[ct] = __builtin_bit_cast(bf16x8, w); }
;                 bf16x8 vf[8];
; #pragma unroll
;                 for (int dt = 0; dt < 8; ++dt) { const LAS unsigned char* vp = vb + (16 * dt + r) * VT_PITCH + (32 * kb2 + 4 * q) * 2;
;                     const s16x4 lo = *(const LAS s16x4*)vp, hi = *(const LAS s16x4*)(vp + 32);
;                     vf[dt] = __builtin_shufflevector(lo, hi, 0, 1, 2, 3, 4, 5, 6, 7); }
;                 __builtin_amdgcn_sched_barrier(0);
; #pragma unroll
;                 for (int dt = 0; dt < 8; ++dt) {
;                     o[0][dt] = __builtin_amdgcn_mfma_f32_16x16x32_bf16(vf[dt], pb[0], o[0][dt], 0, 0, 0);
;                     o[1][dt] = __builtin_amdgcn_mfma_f32_16x16x32_bf16(vf[dt], pb[1], o[1][dt], 0, 0, 0); }
;                 __builtin_amdgcn_sched_barrier(0);
;             }
.Llazy_a_skip:
	ds_read2_b64 v[136:139], v173 offset1:4
	ds_read2_b64 v[140:143], v175 offset0:16 offset1:20
	ds_read2_b64 v[144:147], v183 offset0:32 offset1:36
	ds_read2_b64 v[206:209], v185 offset0:48 offset1:52
	ds_read2_b64 v[210:213], v187 offset0:64 offset1:68
	ds_read2_b64 v[214:217], v189 offset0:80 offset1:84
	ds_read2_b64 v[218:221], v223 offset0:96 offset1:100
	ds_read2_b64 v[226:229], v225 offset0:112 offset1:116
	v_cvt_pk_bf16_f32 v168, v168, v170
	v_cvt_pk_bf16_f32 v169, v172, v174
	v_cvt_pk_bf16_f32 v170, v182, v184
	v_cvt_pk_bf16_f32 v171, v186, v188
	s_waitcnt lgkmcnt(7)
	v_mfma_f32_16x16x32_bf16 v[60:63], v[136:139], v[132:135], v[60:63]
	v_mfma_f32_16x16x32_bf16 v[28:31], v[136:139], v[168:171], v[28:31]
	s_waitcnt lgkmcnt(6)
	v_mfma_f32_16x16x32_bf16 v[56:59], v[140:143], v[132:135], v[56:59]
	v_mfma_f32_16x16x32_bf16 v[24:27], v[140:143], v[168:171], v[24:27]
	s_waitcnt lgkmcnt(5)
	v_mfma_f32_16x16x32_bf16 v[52:55], v[144:147], v[132:135], v[52:55]
	v_mfma_f32_16x16x32_bf16 v[20:23], v[144:147], v[168:171], v[20:23]
	s_waitcnt lgkmcnt(4)
	v_mfma_f32_16x16x32_bf16 v[48:51], v[206:209], v[132:135], v[48:51]
	v_mfma_f32_16x16x32_bf16 v[16:19], v[206:209], v[168:171], v[16:19]
	s_waitcnt lgkmcnt(3)
	v_mfma_f32_16x16x32_bf16 v[44:47], v[210:213], v[132:135], v[44:47]
	v_mfma_f32_16x16x32_bf16 v[12:15], v[210:213], v[168:171], v[12:15]
	s_waitcnt lgkmcnt(2)
	v_mfma_f32_16x16x32_bf16 v[40:43], v[214:217], v[132:135], v[40:43]
	v_mfma_f32_16x16x32_bf16 v[8:11], v[214:217], v[168:171], v[8:11]
	s_waitcnt lgkmcnt(1)
	v_mfma_f32_16x16x32_bf16 v[36:39], v[218:221], v[132:135], v[36:39]
	v_mfma_f32_16x16x32_bf16 v[4:7], v[218:221], v[168:171], v[4:7]
	s_waitcnt lgkmcnt(0)
	v_mfma_f32_16x16x32_bf16 v[32:35], v[226:229], v[132:135], v[32:35]
	v_mfma_f32_16x16x32_bf16 v[0:3], v[226:229], v[168:171], v[0:3]
	ds_read2_b64 v[136:139], v173 offset0:8 offset1:12
	ds_read2_b64 v[140:143], v175 offset0:24 offset1:28
	ds_read2_b64 v[144:147], v183 offset0:40 offset1:44
	ds_read2_b64 v[168:171], v185 offset0:56 offset1:60
	ds_read2_b64 v[172:175], v187 offset0:72 offset1:76
	ds_read2_b64 v[182:185], v189 offset0:88 offset1:92
	ds_read2_b64 v[186:189], v223 offset0:104 offset1:108
	ds_read2_b64 v[206:209], v225 offset0:120 offset1:124
	v_cvt_pk_bf16_f32 v132, v149, v151
	v_cvt_pk_bf16_f32 v133, v157, v159
	v_cvt_pk_bf16_f32 v134, v161, v153
	v_cvt_pk_bf16_f32 v135, v163, v155
	v_cvt_pk_bf16_f32 v148, v148, v150
	v_cvt_pk_bf16_f32 v149, v156, v158
	v_cvt_pk_bf16_f32 v150, v160, v152
	v_cvt_pk_bf16_f32 v151, v162, v154
	s_waitcnt lgkmcnt(7)
	v_mfma_f32_16x16x32_bf16 v[60:63], v[136:139], v[132:135], v[60:63]
	v_mfma_f32_16x16x32_bf16 v[28:31], v[136:139], v[148:151], v[28:31]
	s_waitcnt lgkmcnt(6)
	v_mfma_f32_16x16x32_bf16 v[56:59], v[140:143], v[132:135], v[56:59]
	v_mfma_f32_16x16x32_bf16 v[24:27], v[140:143], v[148:151], v[24:27]
	s_waitcnt lgkmcnt(5)
	v_mfma_f32_16x16x32_bf16 v[52:55], v[144:147], v[132:135], v[52:55]
	v_mfma_f32_16x16x32_bf16 v[20:23], v[144:147], v[148:151], v[20:23]
	s_waitcnt lgkmcnt(4)
	v_mfma_f32_16x16x32_bf16 v[48:51], v[168:171], v[132:135], v[48:51]
	v_mfma_f32_16x16x32_bf16 v[16:19], v[168:171], v[148:151], v[16:19]
	s_waitcnt lgkmcnt(3)
	v_mfma_f32_16x16x32_bf16 v[44:47], v[172:175], v[132:135], v[44:47]
	v_mfma_f32_16x16x32_bf16 v[12:15], v[172:175], v[148:151], v[12:15]
	s_waitcnt lgkmcnt(2)
	v_mfma_f32_16x16x32_bf16 v[40:43], v[182:185], v[132:135], v[40:43]
	v_mfma_f32_16x16x32_bf16 v[8:11], v[182:185], v[148:151], v[8:11]
	s_waitcnt lgkmcnt(1)
	v_mfma_f32_16x16x32_bf16 v[36:39], v[186:189], v[132:135], v[36:39]
	v_mfma_f32_16x16x32_bf16 v[4:7], v[186:189], v[148:151], v[4:7]
	s_waitcnt lgkmcnt(0)
	v_mfma_f32_16x16x32_bf16 v[32:35], v[206:209], v[132:135], v[32:35]
	v_mfma_f32_16x16x32_bf16 v[0:3], v[206:209], v[148:151], v[0:3]
	v_mov_b32_e32 v185, v205
	v_mov_b32_e32 v184, v222

; __global__ void __launch_bounds__(NTHREADS, 2) fwd_megakernel(Args a) {
	.amdhsa_kernel _Z14fwd_megakernel4Args
		.amdhsa_group_segment_fixed_size 0
		.amdhsa_private_segment_fixed_size 0
		.amdhsa_kernarg_size 408
		.amdhsa_user_sgpr_count 2
		.amdhsa_user_sgpr_dispatch_ptr 0
		.amdhsa_user_sgpr_queue_ptr 0
		.amdhsa_user_sgpr_kernarg_segment_ptr 1
		.amdhsa_user_sgpr_dispatch_id 0
		.amdhsa_user_sgpr_kernarg_preload_length 0
		.amdhsa_user_sgpr_kernarg_preload_offset 0
		.amdhsa_user_sgpr_private_segment_size 0
		.amdhsa_uses_dynamic_stack 0
		.amdhsa_enable_private_segment 0
		.amdhsa_system_sgpr_workgroup_id_x 1
		.amdhsa_system_sgpr_workgroup_id_y 0
		.amdhsa_system_sgpr_workgroup_id_z 0
		.amdhsa_system_sgpr_workgroup_info 0
		.amdhsa_system_vgpr_workitem_id 2
		.amdhsa_next_free_vgpr 243
		.amdhsa_next_free_sgpr 102
		.amdhsa_accum_offset 244
		.amdhsa_reserve_vcc 1
		.amdhsa_float_round_mode_32 0
		.amdhsa_float_round_mode_16_64 0
		.amdhsa_float_denorm_mode_32 3
		.amdhsa_float_denorm_mode_16_64 3
		.amdhsa_dx10_clamp 1
		.amdhsa_ieee_mode 1
		.amdhsa_fp16_overflow 0
		.amdhsa_tg_split 0
		.amdhsa_exception_fp_ieee_invalid_op 0
		.amdhsa_exception_fp_denorm_src 0
		.amdhsa_exception_fp_ieee_div_zero 0
		.amdhsa_exception_fp_ieee_overflow 0
		.amdhsa_exception_fp_ieee_underflow 0
		.amdhsa_exception_fp_ieee_inexact 0
		.amdhsa_exception_int_div_zero 0
	.end_amdhsa_kernel

; __global__ void __launch_bounds__(NTHREADS, 2) fwd_megakernel(Args a) {
amdhsa.kernels:
  - .agpr_count:     0
    .args:
      - .offset:         0
        .size:           152
        .value_kind:     by_value
      - .offset:         152
        .size:           4
        .value_kind:     hidden_block_count_x
      - .offset:         156
        .size:           4
        .value_kind:     hidden_block_count_y
      - .offset:         160
        .size:           4
        .value_kind:     hidden_block_count_z
      - .offset:         164
        .size:           2
        .value_kind:     hidden_group_size_x
      - .offset:         166
        .size:           2
        .value_kind:     hidden_group_size_y
      - .offset:         168
        .size:           2
        .value_kind:     hidden_group_size_z
      - .offset:         170
        .size:           2
        .value_kind:     hidden_remainder_x
      - .offset:         172
        .size:           2
        .value_kind:     hidden_remainder_y
      - .offset:         174
        .size:           2
        .value_kind:     hidden_remainder_z
      - .offset:         192
        .size:           8
        .value_kind:     hidden_global_offset_x
      - .offset:         200
        .size:           8
        .value_kind:     hidden_global_offset_y
      - .offset:         208
        .size:           8
        .value_kind:     hidden_global_offset_z
      - .offset:         216
        .size:           2
        .value_kind:     hidden_grid_dims
      - .offset:         240
        .size:           8
        .value_kind:     hidden_multigrid_sync_arg
      - .offset:         272
        .size:           4
        .value_kind:     hidden_dynamic_lds_size
    .group_segment_fixed_size: 0
    .kernarg_segment_align: 8
    .kernarg_segment_size: 408
    .language:       OpenCL C
    .language_version:
      - 2
      - 0
    .max_flat_workgroup_size: 512
    .name:           _Z14fwd_megakernel4Args
    .private_segment_fixed_size: 0
    .sgpr_count:     108
    .sgpr_spill_count: 3
    .symbol:         _Z14fwd_megakernel4Args.kd
    .uniform_work_group_size: 1
    .uses_dynamic_stack: false
    .vgpr_count:     243
    .vgpr_spill_count: 0
    .wavefront_size: 64
